# w_branch/w_out conversion split by layer between the two in-projection slots (10 tiles in each layer's slot instead of 14 / 6)
# baseline (speedup 1.0000x reference)
.LBB0_241:
	s_or_b64 exec, exec, s[0:1]
	v_readlane_b32 s2, v253, 26
	v_readlane_b32 s3, v253, 27
	s_mov_b64 s[0:1], 0
	s_andn2_b64 vcc, exec, s[2:3]
	s_waitcnt lgkmcnt(0)
	s_barrier
	s_cbranch_vccnz .LBB0_243
	v_lshrrev_b32_e32 v120, 4, v197
	v_and_b32_e32 v121, 15, v197
	v_lshlrev_b32_e32 v121, 2, v121
	v_lshl_add_u32 v122, v120, 10, v121
	v_lshlrev_b32_e32 v122, 2, v122
	v_mul_u32_u24_e32 v138, 0x8800, v120
	v_lshl_add_u32 v138, v121, 2, v138
	v_mul_u32_u24_e32 v123, 0x41, v120
	v_add_u32_e32 v123, v123, v121
	v_lshlrev_b32_e32 v123, 2, v123
	v_lshrrev_b32_e32 v124, 3, v197
	v_and_b32_e32 v125, 7, v197
	v_lshlrev_b32_e32 v125, 3, v125
	v_bfe_u32 v127, v124, 2, 2
	v_lshlrev_b32_e32 v127, 3, v127
	v_bfe_u32 v136, v124, 4, 1
	v_lshl_add_u32 v127, v136, 2, v127
	v_and_b32_e32 v136, 3, v124
	v_add_u32_e32 v127, v127, v136
	v_and_b32_e32 v136, 32, v124
	v_add_u32_e32 v127, v127, v136
	v_mul_u32_u24_e32 v136, 0x41, v125
	v_add_u32_e32 v136, v136, v127
	v_lshlrev_b32_e32 v136, 2, v136
	v_lshl_add_u32 v137, v124, 10, v125
	v_lshlrev_b32_e32 v137, 1, v137
	s_sub_i32 s2, s52, 0x80
	v_readlane_b32 s3, v252, 23
	s_nop 3
	s_cmp_eq_u32 s3, 0
	s_cbranch_scc1 .Lcw_l1
	v_readlane_b32 s28, v253, 4
	v_readlane_b32 s29, v253, 5
	v_readlane_b32 s30, v253, 6
	v_readlane_b32 s31, v253, 7
	s_nop 3
	s_add_i32 s4, s2, 0
	s_cmpk_lt_u32 s4, 0x200
	s_cselect_b32 s6, s28, s30
	s_cselect_b32 s7, s29, s31
	s_mov_b32 s16, 0x10500000
	s_cselect_b32 s16, 0x10100000, s16
	s_bfe_u32 s5, s4, 0x10008
	s_lshl_b32 s3, s5, 22
	s_add_u32 s6, s6, s3
	s_addc_u32 s7, s7, 0
	s_lshl_b32 s3, s5, 21
	s_add_i32 s16, s16, s3
	s_and_b32 s3, s4, 15
	s_bfe_u32 s5, s4, 0x40004
	s_lshl_b32 s17, s3, 18
	s_lshl_b32 s20, s5, 8
	s_add_i32 s17, s17, s20
	s_add_u32 s6, s6, s17
	s_addc_u32 s7, s7, 0
	s_add_u32 s12, s6, 0x20000
	s_addc_u32 s13, s7, 0
	s_lshl_b32 s17, s5, 17
	s_lshl_b32 s20, s3, 7
	s_add_i32 s17, s17, s20
	s_add_i32 s16, s16, s17
	s_add_u32 s16, s96, s16
	s_addc_u32 s17, s97, 0
	global_load_dwordx4 v[140:143], v122, s[6:7]
	global_load_dwordx4 v[150:153], v122, s[12:13]
	s_waitcnt vmcnt(0)
	ds_write_b32 v123, v140 offset:0
	ds_write_b32 v123, v141 offset:4
	ds_write_b32 v123, v142 offset:8
	ds_write_b32 v123, v143 offset:12
	ds_write_b32 v123, v150 offset:8320
	ds_write_b32 v123, v151 offset:8324
	ds_write_b32 v123, v152 offset:8328
	ds_write_b32 v123, v153 offset:8332
	s_waitcnt lgkmcnt(0)
	s_barrier
	s_mov_b64 s[26:27], s[16:17]
	s_add_i32 s4, s2, 128
	s_cmpk_lt_u32 s4, 0x200
	s_cselect_b32 s6, s28, s30
	s_cselect_b32 s7, s29, s31
	s_mov_b32 s16, 0x10500000
	s_cselect_b32 s16, 0x10100000, s16
	s_bfe_u32 s5, s4, 0x10008
	s_lshl_b32 s3, s5, 22
	s_add_u32 s6, s6, s3
	s_addc_u32 s7, s7, 0
	s_lshl_b32 s3, s5, 21
	s_add_i32 s16, s16, s3
	s_and_b32 s3, s4, 15
	s_bfe_u32 s5, s4, 0x40004
	s_lshl_b32 s17, s3, 18
	s_lshl_b32 s20, s5, 8
	s_add_i32 s17, s17, s20
	s_add_u32 s6, s6, s17
	s_addc_u32 s7, s7, 0
	s_add_u32 s12, s6, 0x20000
	s_addc_u32 s13, s7, 0
	s_lshl_b32 s17, s5, 17
	s_lshl_b32 s20, s3, 7
	s_add_i32 s17, s17, s20
	s_add_i32 s16, s16, s17
	s_add_u32 s16, s96, s16
	s_addc_u32 s17, s97, 0
	global_load_dwordx4 v[140:143], v122, s[6:7]
	global_load_dwordx4 v[150:153], v122, s[12:13]
	ds_read_b32 v154, v136 offset:0
	ds_read_b32 v155, v136 offset:260
	ds_read_b32 v156, v136 offset:520
	ds_read_b32 v157, v136 offset:780
	ds_read_b32 v158, v136 offset:1040
	ds_read_b32 v159, v136 offset:1300
	ds_read_b32 v160, v136 offset:1560
	ds_read_b32 v161, v136 offset:1820
	s_waitcnt lgkmcnt(0)
	v_cvt_pk_bf16_f32 v204, v154, v155
	v_cvt_pk_bf16_f32 v205, v156, v157
	v_cvt_pk_bf16_f32 v206, v158, v159
	v_cvt_pk_bf16_f32 v207, v160, v161
	global_store_dwordx4 v137, v[204:207], s[26:27]
	s_barrier
	s_waitcnt vmcnt(0)
	ds_write_b32 v123, v140 offset:0
	ds_write_b32 v123, v141 offset:4
	ds_write_b32 v123, v142 offset:8
	ds_write_b32 v123, v143 offset:12
	ds_write_b32 v123, v150 offset:8320
	ds_write_b32 v123, v151 offset:8324
	ds_write_b32 v123, v152 offset:8328
	ds_write_b32 v123, v153 offset:8332
	s_waitcnt lgkmcnt(0)
	s_barrier
	s_mov_b64 s[26:27], s[16:17]
	s_add_i32 s4, s2, 512
	s_cmpk_lt_u32 s4, 0x200
	s_cselect_b32 s6, s28, s30
	s_cselect_b32 s7, s29, s31
	s_mov_b32 s16, 0x10500000
	s_cselect_b32 s16, 0x10100000, s16
	s_bfe_u32 s5, s4, 0x10008
	s_lshl_b32 s3, s5, 22
	s_add_u32 s6, s6, s3
	s_addc_u32 s7, s7, 0
	s_lshl_b32 s3, s5, 21
	s_add_i32 s16, s16, s3
	s_and_b32 s3, s4, 15
	s_bfe_u32 s5, s4, 0x40004
	s_lshl_b32 s17, s3, 18
	s_lshl_b32 s20, s5, 8
	s_add_i32 s17, s17, s20
	s_add_u32 s6, s6, s17
	s_addc_u32 s7, s7, 0
	s_add_u32 s12, s6, 0x20000
	s_addc_u32 s13, s7, 0
	s_lshl_b32 s17, s5, 17
	s_lshl_b32 s20, s3, 7
	s_add_i32 s17, s17, s20
	s_add_i32 s16, s16, s17
	s_add_u32 s16, s96, s16
	s_addc_u32 s17, s97, 0
	global_load_dwordx4 v[140:143], v122, s[6:7]
	global_load_dwordx4 v[150:153], v122, s[12:13]
	ds_read_b32 v154, v136 offset:0
	ds_read_b32 v155, v136 offset:260
	ds_read_b32 v156, v136 offset:520
	ds_read_b32 v157, v136 offset:780
	ds_read_b32 v158, v136 offset:1040
	ds_read_b32 v159, v136 offset:1300
	ds_read_b32 v160, v136 offset:1560
	ds_read_b32 v161, v136 offset:1820
	s_waitcnt lgkmcnt(0)
	v_cvt_pk_bf16_f32 v204, v154, v155
	v_cvt_pk_bf16_f32 v205, v156, v157
	v_cvt_pk_bf16_f32 v206, v158, v159
	v_cvt_pk_bf16_f32 v207, v160, v161
	global_store_dwordx4 v137, v[204:207], s[26:27]
	s_barrier
	s_waitcnt vmcnt(0)
	ds_write_b32 v123, v140 offset:0
	ds_write_b32 v123, v141 offset:4
	ds_write_b32 v123, v142 offset:8
	ds_write_b32 v123, v143 offset:12
	ds_write_b32 v123, v150 offset:8320
	ds_write_b32 v123, v151 offset:8324
	ds_write_b32 v123, v152 offset:8328
	ds_write_b32 v123, v153 offset:8332
	s_waitcnt lgkmcnt(0)
	s_barrier
	s_mov_b64 s[26:27], s[16:17]
	s_add_i32 s4, s2, 640
	s_cmpk_lt_u32 s4, 0x200
	s_cselect_b32 s6, s28, s30
	s_cselect_b32 s7, s29, s31
	s_mov_b32 s16, 0x10500000
	s_cselect_b32 s16, 0x10100000, s16
	s_bfe_u32 s5, s4, 0x10008
	s_lshl_b32 s3, s5, 22
	s_add_u32 s6, s6, s3
	s_addc_u32 s7, s7, 0
	s_lshl_b32 s3, s5, 21
	s_add_i32 s16, s16, s3
	s_and_b32 s3, s4, 15
	s_bfe_u32 s5, s4, 0x40004
	s_lshl_b32 s17, s3, 18
	s_lshl_b32 s20, s5, 8
	s_add_i32 s17, s17, s20
	s_add_u32 s6, s6, s17
	s_addc_u32 s7, s7, 0
	s_add_u32 s12, s6, 0x20000
	s_addc_u32 s13, s7, 0
	s_lshl_b32 s17, s5, 17
	s_lshl_b32 s20, s3, 7
	s_add_i32 s17, s17, s20
	s_add_i32 s16, s16, s17
	s_add_u32 s16, s96, s16
	s_addc_u32 s17, s97, 0
	global_load_dwordx4 v[140:143], v122, s[6:7]
	global_load_dwordx4 v[150:153], v122, s[12:13]
	ds_read_b32 v154, v136 offset:0
	ds_read_b32 v155, v136 offset:260
	ds_read_b32 v156, v136 offset:520
	ds_read_b32 v157, v136 offset:780
	ds_read_b32 v158, v136 offset:1040
	ds_read_b32 v159, v136 offset:1300
	ds_read_b32 v160, v136 offset:1560
	ds_read_b32 v161, v136 offset:1820
	s_waitcnt lgkmcnt(0)
	v_cvt_pk_bf16_f32 v204, v154, v155
	v_cvt_pk_bf16_f32 v205, v156, v157
	v_cvt_pk_bf16_f32 v206, v158, v159
	v_cvt_pk_bf16_f32 v207, v160, v161
	global_store_dwordx4 v137, v[204:207], s[26:27]
	s_barrier
	s_waitcnt vmcnt(0)
	ds_write_b32 v123, v140 offset:0
	ds_write_b32 v123, v141 offset:4
	ds_write_b32 v123, v142 offset:8
	ds_write_b32 v123, v143 offset:12
	ds_write_b32 v123, v150 offset:8320
	ds_write_b32 v123, v151 offset:8324
	ds_write_b32 v123, v152 offset:8328
	ds_write_b32 v123, v153 offset:8332
	s_waitcnt lgkmcnt(0)
	s_barrier
	s_mov_b64 s[26:27], s[16:17]
	ds_read_b32 v154, v136 offset:0
	ds_read_b32 v155, v136 offset:260
	ds_read_b32 v156, v136 offset:520
	ds_read_b32 v157, v136 offset:780
	ds_read_b32 v158, v136 offset:1040
	ds_read_b32 v159, v136 offset:1300
	ds_read_b32 v160, v136 offset:1560
	ds_read_b32 v161, v136 offset:1820
	s_waitcnt lgkmcnt(0)
	v_cvt_pk_bf16_f32 v204, v154, v155
	v_cvt_pk_bf16_f32 v205, v156, v157
	v_cvt_pk_bf16_f32 v206, v158, v159
	v_cvt_pk_bf16_f32 v207, v160, v161
	global_store_dwordx4 v137, v[204:207], s[26:27]
	s_barrier
	v_readlane_b32 s28, v253, 20
	v_readlane_b32 s29, v253, 21
	s_nop 3
	s_add_i32 s4, s2, 1408
	s_and_b32 s3, s4, 15
	s_lshr_b32 s5, s4, 4
	s_mul_i32 s17, s3, 0x220000
	s_lshl_b32 s20, s5, 8
	s_add_i32 s17, s17, s20
	s_add_u32 s6, s28, s17
	s_addc_u32 s7, s29, 0
	s_add_u32 s12, s6, 0x110000
	s_addc_u32 s13, s7, 0
	s_lshl_b32 s17, s5, 17
	s_lshl_b32 s20, s3, 7
	s_add_i32 s17, s17, s20
	s_add_u32 s16, s96, s17
	s_addc_u32 s17, s97, 0
	s_add_u32 s16, s16, 0xf000000
	s_addc_u32 s17, s17, 0
	global_load_dwordx4 v[140:143], v138, s[6:7]
	global_load_dwordx4 v[150:153], v138, s[12:13]
	s_waitcnt vmcnt(0)
	ds_write_b32 v123, v140 offset:0
	ds_write_b32 v123, v141 offset:4
	ds_write_b32 v123, v142 offset:8
	ds_write_b32 v123, v143 offset:12
	ds_write_b32 v123, v150 offset:8320
	ds_write_b32 v123, v151 offset:8324
	ds_write_b32 v123, v152 offset:8328
	ds_write_b32 v123, v153 offset:8332
	s_waitcnt lgkmcnt(0)
	s_barrier
	s_mov_b64 s[26:27], s[16:17]
	s_add_i32 s4, s2, 1536
	s_and_b32 s3, s4, 15
	s_lshr_b32 s5, s4, 4
	s_mul_i32 s17, s3, 0x220000
	s_lshl_b32 s20, s5, 8
	s_add_i32 s17, s17, s20
	s_add_u32 s6, s28, s17
	s_addc_u32 s7, s29, 0
	s_add_u32 s12, s6, 0x110000
	s_addc_u32 s13, s7, 0
	s_lshl_b32 s17, s5, 17
	s_lshl_b32 s20, s3, 7
	s_add_i32 s17, s17, s20
	s_add_u32 s16, s96, s17
	s_addc_u32 s17, s97, 0
	s_add_u32 s16, s16, 0xf000000
	s_addc_u32 s17, s17, 0
	global_load_dwordx4 v[140:143], v138, s[6:7]
	global_load_dwordx4 v[150:153], v138, s[12:13]
	ds_read_b32 v154, v136 offset:0
	ds_read_b32 v155, v136 offset:260
	ds_read_b32 v156, v136 offset:520
	ds_read_b32 v157, v136 offset:780
	ds_read_b32 v158, v136 offset:1040
	ds_read_b32 v159, v136 offset:1300
	ds_read_b32 v160, v136 offset:1560
	ds_read_b32 v161, v136 offset:1820
	s_waitcnt lgkmcnt(0)
	v_mul_f32_e32 v154, v235, v154
	v_mul_f32_e32 v155, v235, v155
	v_mul_f32_e32 v156, v235, v156
	v_mul_f32_e32 v157, v235, v157
	v_mul_f32_e32 v158, v235, v158
	v_mul_f32_e32 v159, v235, v159
	v_mul_f32_e32 v160, v235, v160
	v_mul_f32_e32 v161, v235, v161
	v_cvt_pk_bf16_f32 v204, v154, v155
	v_cvt_pk_bf16_f32 v205, v156, v157
	v_cvt_pk_bf16_f32 v206, v158, v159
	v_cvt_pk_bf16_f32 v207, v160, v161
	global_store_dwordx4 v137, v[204:207], s[26:27]
	s_barrier
	s_waitcnt vmcnt(0)
	ds_write_b32 v123, v140 offset:0
	ds_write_b32 v123, v141 offset:4
	ds_write_b32 v123, v142 offset:8
	ds_write_b32 v123, v143 offset:12
	ds_write_b32 v123, v150 offset:8320
	ds_write_b32 v123, v151 offset:8324
	ds_write_b32 v123, v152 offset:8328
	ds_write_b32 v123, v153 offset:8332
	s_waitcnt lgkmcnt(0)
	s_barrier
	s_mov_b64 s[26:27], s[16:17]
	s_add_i32 s4, s2, 1664
	s_and_b32 s3, s4, 15
	s_lshr_b32 s5, s4, 4
	s_mul_i32 s17, s3, 0x220000
	s_lshl_b32 s20, s5, 8
	s_add_i32 s17, s17, s20
	s_add_u32 s6, s28, s17
	s_addc_u32 s7, s29, 0
	s_add_u32 s12, s6, 0x110000
	s_addc_u32 s13, s7, 0
	s_lshl_b32 s17, s5, 17
	s_lshl_b32 s20, s3, 7
	s_add_i32 s17, s17, s20
	s_add_u32 s16, s96, s17
	s_addc_u32 s17, s97, 0
	s_add_u32 s16, s16, 0xf000000
	s_addc_u32 s17, s17, 0
	global_load_dwordx4 v[140:143], v138, s[6:7]
	global_load_dwordx4 v[150:153], v138, s[12:13]
	ds_read_b32 v154, v136 offset:0
	ds_read_b32 v155, v136 offset:260
	ds_read_b32 v156, v136 offset:520
	ds_read_b32 v157, v136 offset:780
	ds_read_b32 v158, v136 offset:1040
	ds_read_b32 v159, v136 offset:1300
	ds_read_b32 v160, v136 offset:1560
	ds_read_b32 v161, v136 offset:1820
	s_waitcnt lgkmcnt(0)
	v_mul_f32_e32 v154, v235, v154
	v_mul_f32_e32 v155, v235, v155
	v_mul_f32_e32 v156, v235, v156
	v_mul_f32_e32 v157, v235, v157
	v_mul_f32_e32 v158, v235, v158
	v_mul_f32_e32 v159, v235, v159
	v_mul_f32_e32 v160, v235, v160
	v_mul_f32_e32 v161, v235, v161
	v_cvt_pk_bf16_f32 v204, v154, v155
	v_cvt_pk_bf16_f32 v205, v156, v157
	v_cvt_pk_bf16_f32 v206, v158, v159
	v_cvt_pk_bf16_f32 v207, v160, v161
	global_store_dwordx4 v137, v[204:207], s[26:27]
	s_barrier
	s_waitcnt vmcnt(0)
	ds_write_b32 v123, v140 offset:0
	ds_write_b32 v123, v141 offset:4
	ds_write_b32 v123, v142 offset:8
	ds_write_b32 v123, v143 offset:12
	ds_write_b32 v123, v150 offset:8320
	ds_write_b32 v123, v151 offset:8324
	ds_write_b32 v123, v152 offset:8328
	ds_write_b32 v123, v153 offset:8332
	s_waitcnt lgkmcnt(0)
	s_barrier
	s_mov_b64 s[26:27], s[16:17]
	s_add_i32 s4, s2, 1792
	s_and_b32 s3, s4, 15
	s_lshr_b32 s5, s4, 4
	s_mul_i32 s17, s3, 0x220000
	s_lshl_b32 s20, s5, 8
	s_add_i32 s17, s17, s20
	s_add_u32 s6, s28, s17
	s_addc_u32 s7, s29, 0
	s_add_u32 s12, s6, 0x110000
	s_addc_u32 s13, s7, 0
	s_lshl_b32 s17, s5, 17
	s_lshl_b32 s20, s3, 7
	s_add_i32 s17, s17, s20
	s_add_u32 s16, s96, s17
	s_addc_u32 s17, s97, 0
	s_add_u32 s16, s16, 0xf000000
	s_addc_u32 s17, s17, 0
	global_load_dwordx4 v[140:143], v138, s[6:7]
	global_load_dwordx4 v[150:153], v138, s[12:13]
	ds_read_b32 v154, v136 offset:0
	ds_read_b32 v155, v136 offset:260
	ds_read_b32 v156, v136 offset:520
	ds_read_b32 v157, v136 offset:780
	ds_read_b32 v158, v136 offset:1040
	ds_read_b32 v159, v136 offset:1300
	ds_read_b32 v160, v136 offset:1560
	ds_read_b32 v161, v136 offset:1820
	s_waitcnt lgkmcnt(0)
	v_mul_f32_e32 v154, v235, v154
	v_mul_f32_e32 v155, v235, v155
	v_mul_f32_e32 v156, v235, v156
	v_mul_f32_e32 v157, v235, v157
	v_mul_f32_e32 v158, v235, v158
	v_mul_f32_e32 v159, v235, v159
	v_mul_f32_e32 v160, v235, v160
	v_mul_f32_e32 v161, v235, v161
	v_cvt_pk_bf16_f32 v204, v154, v155
	v_cvt_pk_bf16_f32 v205, v156, v157
	v_cvt_pk_bf16_f32 v206, v158, v159
	v_cvt_pk_bf16_f32 v207, v160, v161
	global_store_dwordx4 v137, v[204:207], s[26:27]
	s_barrier
	s_waitcnt vmcnt(0)
	ds_write_b32 v123, v140 offset:0
	ds_write_b32 v123, v141 offset:4
	ds_write_b32 v123, v142 offset:8
	ds_write_b32 v123, v143 offset:12
	ds_write_b32 v123, v150 offset:8320
	ds_write_b32 v123, v151 offset:8324
	ds_write_b32 v123, v152 offset:8328
	ds_write_b32 v123, v153 offset:8332
	s_waitcnt lgkmcnt(0)
	s_barrier
	s_mov_b64 s[26:27], s[16:17]
	s_add_i32 s4, s2, 1920
	s_and_b32 s3, s4, 15
	s_lshr_b32 s5, s4, 4
	s_mul_i32 s17, s3, 0x220000
	s_lshl_b32 s20, s5, 8
	s_add_i32 s17, s17, s20
	s_add_u32 s6, s28, s17
	s_addc_u32 s7, s29, 0
	s_add_u32 s12, s6, 0x110000
	s_addc_u32 s13, s7, 0
	s_lshl_b32 s17, s5, 17
	s_lshl_b32 s20, s3, 7
	s_add_i32 s17, s17, s20
	s_add_u32 s16, s96, s17
	s_addc_u32 s17, s97, 0
	s_add_u32 s16, s16, 0xf000000
	s_addc_u32 s17, s17, 0
	global_load_dwordx4 v[140:143], v138, s[6:7]
	global_load_dwordx4 v[150:153], v138, s[12:13]
	ds_read_b32 v154, v136 offset:0
	ds_read_b32 v155, v136 offset:260
	ds_read_b32 v156, v136 offset:520
	ds_read_b32 v157, v136 offset:780
	ds_read_b32 v158, v136 offset:1040
	ds_read_b32 v159, v136 offset:1300
	ds_read_b32 v160, v136 offset:1560
	ds_read_b32 v161, v136 offset:1820
	s_waitcnt lgkmcnt(0)
	v_mul_f32_e32 v154, v235, v154
	v_mul_f32_e32 v155, v235, v155
	v_mul_f32_e32 v156, v235, v156
	v_mul_f32_e32 v157, v235, v157
	v_mul_f32_e32 v158, v235, v158
	v_mul_f32_e32 v159, v235, v159
	v_mul_f32_e32 v160, v235, v160
	v_mul_f32_e32 v161, v235, v161
	v_cvt_pk_bf16_f32 v204, v154, v155
	v_cvt_pk_bf16_f32 v205, v156, v157
	v_cvt_pk_bf16_f32 v206, v158, v159
	v_cvt_pk_bf16_f32 v207, v160, v161
	global_store_dwordx4 v137, v[204:207], s[26:27]
	s_barrier
	s_waitcnt vmcnt(0)
	ds_write_b32 v123, v140 offset:0
	ds_write_b32 v123, v141 offset:4
	ds_write_b32 v123, v142 offset:8
	ds_write_b32 v123, v143 offset:12
	ds_write_b32 v123, v150 offset:8320
	ds_write_b32 v123, v151 offset:8324
	ds_write_b32 v123, v152 offset:8328
	ds_write_b32 v123, v153 offset:8332
	s_waitcnt lgkmcnt(0)
	s_barrier
	s_mov_b64 s[26:27], s[16:17]
	s_add_i32 s4, s2, 2048
	s_and_b32 s3, s4, 15
	s_lshr_b32 s5, s4, 4
	s_mul_i32 s17, s3, 0x220000
	s_lshl_b32 s20, s5, 8
	s_add_i32 s17, s17, s20
	s_add_u32 s6, s28, s17
	s_addc_u32 s7, s29, 0
	s_add_u32 s12, s6, 0x110000
	s_addc_u32 s13, s7, 0
	s_lshl_b32 s17, s5, 17
	s_lshl_b32 s20, s3, 7
	s_add_i32 s17, s17, s20
	s_add_u32 s16, s96, s17
	s_addc_u32 s17, s97, 0
	s_add_u32 s16, s16, 0xf000000
	s_addc_u32 s17, s17, 0
	global_load_dwordx4 v[140:143], v138, s[6:7]
	global_load_dwordx4 v[150:153], v138, s[12:13]
	ds_read_b32 v154, v136 offset:0
	ds_read_b32 v155, v136 offset:260
	ds_read_b32 v156, v136 offset:520
	ds_read_b32 v157, v136 offset:780
	ds_read_b32 v158, v136 offset:1040
	ds_read_b32 v159, v136 offset:1300
	ds_read_b32 v160, v136 offset:1560
	ds_read_b32 v161, v136 offset:1820
	s_waitcnt lgkmcnt(0)
	v_mul_f32_e32 v154, v235, v154
	v_mul_f32_e32 v155, v235, v155
	v_mul_f32_e32 v156, v235, v156
	v_mul_f32_e32 v157, v235, v157
	v_mul_f32_e32 v158, v235, v158
	v_mul_f32_e32 v159, v235, v159
	v_mul_f32_e32 v160, v235, v160
	v_mul_f32_e32 v161, v235, v161
	v_cvt_pk_bf16_f32 v204, v154, v155
	v_cvt_pk_bf16_f32 v205, v156, v157
	v_cvt_pk_bf16_f32 v206, v158, v159
	v_cvt_pk_bf16_f32 v207, v160, v161
	global_store_dwordx4 v137, v[204:207], s[26:27]
	s_barrier
	s_waitcnt vmcnt(0)
	ds_write_b32 v123, v140 offset:0
	ds_write_b32 v123, v141 offset:4
	ds_write_b32 v123, v142 offset:8
	ds_write_b32 v123, v143 offset:12
	ds_write_b32 v123, v150 offset:8320
	ds_write_b32 v123, v151 offset:8324
	ds_write_b32 v123, v152 offset:8328
	ds_write_b32 v123, v153 offset:8332
	s_waitcnt lgkmcnt(0)
	s_barrier
	s_mov_b64 s[26:27], s[16:17]
	ds_read_b32 v154, v136 offset:0
	ds_read_b32 v155, v136 offset:260
	ds_read_b32 v156, v136 offset:520
	ds_read_b32 v157, v136 offset:780
	ds_read_b32 v158, v136 offset:1040
	ds_read_b32 v159, v136 offset:1300
	ds_read_b32 v160, v136 offset:1560
	ds_read_b32 v161, v136 offset:1820
	s_waitcnt lgkmcnt(0)
	v_mul_f32_e32 v154, v235, v154
	v_mul_f32_e32 v155, v235, v155
	v_mul_f32_e32 v156, v235, v156
	v_mul_f32_e32 v157, v235, v157
	v_mul_f32_e32 v158, v235, v158
	v_mul_f32_e32 v159, v235, v159
	v_mul_f32_e32 v160, v235, v160
	v_mul_f32_e32 v161, v235, v161
	v_cvt_pk_bf16_f32 v204, v154, v155
	v_cvt_pk_bf16_f32 v205, v156, v157
	v_cvt_pk_bf16_f32 v206, v158, v159
	v_cvt_pk_bf16_f32 v207, v160, v161
	global_store_dwordx4 v137, v[204:207], s[26:27]
	s_barrier
	s_branch .LBB0_243
.Lcw_l1:
	v_readlane_b32 s28, v253, 20
	v_readlane_b32 s29, v253, 21
	s_nop 3
	s_add_u32 s28, s28, 0x2200000
	s_addc_u32 s29, s29, 0
	s_add_i32 s4, s2, 1408
	s_and_b32 s3, s4, 15
	s_lshr_b32 s5, s4, 4
	s_mul_i32 s17, s3, 0x220000
	s_lshl_b32 s20, s5, 8
	s_add_i32 s17, s17, s20
	s_add_u32 s6, s28, s17
	s_addc_u32 s7, s29, 0
	s_add_u32 s12, s6, 0x110000
	s_addc_u32 s13, s7, 0
	s_lshl_b32 s17, s5, 17
	s_lshl_b32 s20, s3, 7
	s_add_i32 s17, s17, s20
	s_add_u32 s16, s96, s17
	s_addc_u32 s17, s97, 0
	s_add_u32 s16, s16, 0xf000000
	s_addc_u32 s17, s17, 0
	global_load_dwordx4 v[140:143], v138, s[6:7]
	global_load_dwordx4 v[150:153], v138, s[12:13]
	s_waitcnt vmcnt(0)
	ds_write_b32 v123, v140 offset:0
	ds_write_b32 v123, v141 offset:4
	ds_write_b32 v123, v142 offset:8
	ds_write_b32 v123, v143 offset:12
	ds_write_b32 v123, v150 offset:8320
	ds_write_b32 v123, v151 offset:8324
	ds_write_b32 v123, v152 offset:8328
	ds_write_b32 v123, v153 offset:8332
	s_waitcnt lgkmcnt(0)
	s_barrier
	s_mov_b64 s[26:27], s[16:17]
	s_add_i32 s4, s2, 1536
	s_and_b32 s3, s4, 15
	s_lshr_b32 s5, s4, 4
	s_mul_i32 s17, s3, 0x220000
	s_lshl_b32 s20, s5, 8
	s_add_i32 s17, s17, s20
	s_add_u32 s6, s28, s17
	s_addc_u32 s7, s29, 0
	s_add_u32 s12, s6, 0x110000
	s_addc_u32 s13, s7, 0
	s_lshl_b32 s17, s5, 17
	s_lshl_b32 s20, s3, 7
	s_add_i32 s17, s17, s20
	s_add_u32 s16, s96, s17
	s_addc_u32 s17, s97, 0
	s_add_u32 s16, s16, 0xf000000
	s_addc_u32 s17, s17, 0
	global_load_dwordx4 v[140:143], v138, s[6:7]
	global_load_dwordx4 v[150:153], v138, s[12:13]
	ds_read_b32 v154, v136 offset:0
	ds_read_b32 v155, v136 offset:260
	ds_read_b32 v156, v136 offset:520
	ds_read_b32 v157, v136 offset:780
	ds_read_b32 v158, v136 offset:1040
	ds_read_b32 v159, v136 offset:1300
	ds_read_b32 v160, v136 offset:1560
	ds_read_b32 v161, v136 offset:1820
	s_waitcnt lgkmcnt(0)
	v_mul_f32_e32 v154, v235, v154
	v_mul_f32_e32 v155, v235, v155
	v_mul_f32_e32 v156, v235, v156
	v_mul_f32_e32 v157, v235, v157
	v_mul_f32_e32 v158, v235, v158
	v_mul_f32_e32 v159, v235, v159
	v_mul_f32_e32 v160, v235, v160
	v_mul_f32_e32 v161, v235, v161
	v_cvt_pk_bf16_f32 v204, v154, v155
	v_cvt_pk_bf16_f32 v205, v156, v157
	v_cvt_pk_bf16_f32 v206, v158, v159
	v_cvt_pk_bf16_f32 v207, v160, v161
	global_store_dwordx4 v137, v[204:207], s[26:27]
	s_barrier
	s_waitcnt vmcnt(0)
	ds_write_b32 v123, v140 offset:0
	ds_write_b32 v123, v141 offset:4
	ds_write_b32 v123, v142 offset:8
	ds_write_b32 v123, v143 offset:12
	ds_write_b32 v123, v150 offset:8320
	ds_write_b32 v123, v151 offset:8324
	ds_write_b32 v123, v152 offset:8328
	ds_write_b32 v123, v153 offset:8332
	s_waitcnt lgkmcnt(0)
	s_barrier
	s_mov_b64 s[26:27], s[16:17]
	s_add_i32 s4, s2, 1664
	s_and_b32 s3, s4, 15
	s_lshr_b32 s5, s4, 4
	s_mul_i32 s17, s3, 0x220000
	s_lshl_b32 s20, s5, 8
	s_add_i32 s17, s17, s20
	s_add_u32 s6, s28, s17
	s_addc_u32 s7, s29, 0
	s_add_u32 s12, s6, 0x110000
	s_addc_u32 s13, s7, 0
	s_lshl_b32 s17, s5, 17
	s_lshl_b32 s20, s3, 7
	s_add_i32 s17, s17, s20
	s_add_u32 s16, s96, s17
	s_addc_u32 s17, s97, 0
	s_add_u32 s16, s16, 0xf000000
	s_addc_u32 s17, s17, 0
	global_load_dwordx4 v[140:143], v138, s[6:7]
	global_load_dwordx4 v[150:153], v138, s[12:13]
	ds_read_b32 v154, v136 offset:0
	ds_read_b32 v155, v136 offset:260
	ds_read_b32 v156, v136 offset:520
	ds_read_b32 v157, v136 offset:780
	ds_read_b32 v158, v136 offset:1040
	ds_read_b32 v159, v136 offset:1300
	ds_read_b32 v160, v136 offset:1560
	ds_read_b32 v161, v136 offset:1820
	s_waitcnt lgkmcnt(0)
	v_mul_f32_e32 v154, v235, v154
	v_mul_f32_e32 v155, v235, v155
	v_mul_f32_e32 v156, v235, v156
	v_mul_f32_e32 v157, v235, v157
	v_mul_f32_e32 v158, v235, v158
	v_mul_f32_e32 v159, v235, v159
	v_mul_f32_e32 v160, v235, v160
	v_mul_f32_e32 v161, v235, v161
	v_cvt_pk_bf16_f32 v204, v154, v155
	v_cvt_pk_bf16_f32 v205, v156, v157
	v_cvt_pk_bf16_f32 v206, v158, v159
	v_cvt_pk_bf16_f32 v207, v160, v161
	global_store_dwordx4 v137, v[204:207], s[26:27]
	s_barrier
	s_waitcnt vmcnt(0)
	ds_write_b32 v123, v140 offset:0
	ds_write_b32 v123, v141 offset:4
	ds_write_b32 v123, v142 offset:8
	ds_write_b32 v123, v143 offset:12
	ds_write_b32 v123, v150 offset:8320
	ds_write_b32 v123, v151 offset:8324
	ds_write_b32 v123, v152 offset:8328
	ds_write_b32 v123, v153 offset:8332
	s_waitcnt lgkmcnt(0)
	s_barrier
	s_mov_b64 s[26:27], s[16:17]
	s_add_i32 s4, s2, 1792
	s_and_b32 s3, s4, 15
	s_lshr_b32 s5, s4, 4
	s_mul_i32 s17, s3, 0x220000
	s_lshl_b32 s20, s5, 8
	s_add_i32 s17, s17, s20
	s_add_u32 s6, s28, s17
	s_addc_u32 s7, s29, 0
	s_add_u32 s12, s6, 0x110000
	s_addc_u32 s13, s7, 0
	s_lshl_b32 s17, s5, 17
	s_lshl_b32 s20, s3, 7
	s_add_i32 s17, s17, s20
	s_add_u32 s16, s96, s17
	s_addc_u32 s17, s97, 0
	s_add_u32 s16, s16, 0xf000000
	s_addc_u32 s17, s17, 0
	global_load_dwordx4 v[140:143], v138, s[6:7]
	global_load_dwordx4 v[150:153], v138, s[12:13]
	ds_read_b32 v154, v136 offset:0
	ds_read_b32 v155, v136 offset:260
	ds_read_b32 v156, v136 offset:520
	ds_read_b32 v157, v136 offset:780
	ds_read_b32 v158, v136 offset:1040
	ds_read_b32 v159, v136 offset:1300
	ds_read_b32 v160, v136 offset:1560
	ds_read_b32 v161, v136 offset:1820
	s_waitcnt lgkmcnt(0)
	v_mul_f32_e32 v154, v235, v154
	v_mul_f32_e32 v155, v235, v155
	v_mul_f32_e32 v156, v235, v156
	v_mul_f32_e32 v157, v235, v157
	v_mul_f32_e32 v158, v235, v158
	v_mul_f32_e32 v159, v235, v159
	v_mul_f32_e32 v160, v235, v160
	v_mul_f32_e32 v161, v235, v161
	v_cvt_pk_bf16_f32 v204, v154, v155
	v_cvt_pk_bf16_f32 v205, v156, v157
	v_cvt_pk_bf16_f32 v206, v158, v159
	v_cvt_pk_bf16_f32 v207, v160, v161
	global_store_dwordx4 v137, v[204:207], s[26:27]
	s_barrier
	s_waitcnt vmcnt(0)
	ds_write_b32 v123, v140 offset:0
	ds_write_b32 v123, v141 offset:4
	ds_write_b32 v123, v142 offset:8
	ds_write_b32 v123, v143 offset:12
	ds_write_b32 v123, v150 offset:8320
	ds_write_b32 v123, v151 offset:8324
	ds_write_b32 v123, v152 offset:8328
	ds_write_b32 v123, v153 offset:8332
	s_waitcnt lgkmcnt(0)
	s_barrier
	s_mov_b64 s[26:27], s[16:17]
	s_add_i32 s4, s2, 1920
	s_and_b32 s3, s4, 15
	s_lshr_b32 s5, s4, 4
	s_mul_i32 s17, s3, 0x220000
	s_lshl_b32 s20, s5, 8
	s_add_i32 s17, s17, s20
	s_add_u32 s6, s28, s17
	s_addc_u32 s7, s29, 0
	s_add_u32 s12, s6, 0x110000
	s_addc_u32 s13, s7, 0
	s_lshl_b32 s17, s5, 17
	s_lshl_b32 s20, s3, 7
	s_add_i32 s17, s17, s20
	s_add_u32 s16, s96, s17
	s_addc_u32 s17, s97, 0
	s_add_u32 s16, s16, 0xf000000
	s_addc_u32 s17, s17, 0
	global_load_dwordx4 v[140:143], v138, s[6:7]
	global_load_dwordx4 v[150:153], v138, s[12:13]
	ds_read_b32 v154, v136 offset:0
	ds_read_b32 v155, v136 offset:260
	ds_read_b32 v156, v136 offset:520
	ds_read_b32 v157, v136 offset:780
	ds_read_b32 v158, v136 offset:1040
	ds_read_b32 v159, v136 offset:1300
	ds_read_b32 v160, v136 offset:1560
	ds_read_b32 v161, v136 offset:1820
	s_waitcnt lgkmcnt(0)
	v_mul_f32_e32 v154, v235, v154
	v_mul_f32_e32 v155, v235, v155
	v_mul_f32_e32 v156, v235, v156
	v_mul_f32_e32 v157, v235, v157
	v_mul_f32_e32 v158, v235, v158
	v_mul_f32_e32 v159, v235, v159
	v_mul_f32_e32 v160, v235, v160
	v_mul_f32_e32 v161, v235, v161
	v_cvt_pk_bf16_f32 v204, v154, v155
	v_cvt_pk_bf16_f32 v205, v156, v157
	v_cvt_pk_bf16_f32 v206, v158, v159
	v_cvt_pk_bf16_f32 v207, v160, v161
	global_store_dwordx4 v137, v[204:207], s[26:27]
	s_barrier
	s_waitcnt vmcnt(0)
	ds_write_b32 v123, v140 offset:0
	ds_write_b32 v123, v141 offset:4
	ds_write_b32 v123, v142 offset:8
	ds_write_b32 v123, v143 offset:12
	ds_write_b32 v123, v150 offset:8320
	ds_write_b32 v123, v151 offset:8324
	ds_write_b32 v123, v152 offset:8328
	ds_write_b32 v123, v153 offset:8332
	s_waitcnt lgkmcnt(0)
	s_barrier
	s_mov_b64 s[26:27], s[16:17]
	s_add_i32 s4, s2, 2048
	s_and_b32 s3, s4, 15
	s_lshr_b32 s5, s4, 4
	s_mul_i32 s17, s3, 0x220000
	s_lshl_b32 s20, s5, 8
	s_add_i32 s17, s17, s20
	s_add_u32 s6, s28, s17
	s_addc_u32 s7, s29, 0
	s_add_u32 s12, s6, 0x110000
	s_addc_u32 s13, s7, 0
	s_lshl_b32 s17, s5, 17
	s_lshl_b32 s20, s3, 7
	s_add_i32 s17, s17, s20
	s_add_u32 s16, s96, s17
	s_addc_u32 s17, s97, 0
	s_add_u32 s16, s16, 0xf000000
	s_addc_u32 s17, s17, 0
	global_load_dwordx4 v[140:143], v138, s[6:7]
	global_load_dwordx4 v[150:153], v138, s[12:13]
	ds_read_b32 v154, v136 offset:0
	ds_read_b32 v155, v136 offset:260
	ds_read_b32 v156, v136 offset:520
	ds_read_b32 v157, v136 offset:780
	ds_read_b32 v158, v136 offset:1040
	ds_read_b32 v159, v136 offset:1300
	ds_read_b32 v160, v136 offset:1560
	ds_read_b32 v161, v136 offset:1820
	s_waitcnt lgkmcnt(0)
	v_mul_f32_e32 v154, v235, v154
	v_mul_f32_e32 v155, v235, v155
	v_mul_f32_e32 v156, v235, v156
	v_mul_f32_e32 v157, v235, v157
	v_mul_f32_e32 v158, v235, v158
	v_mul_f32_e32 v159, v235, v159
	v_mul_f32_e32 v160, v235, v160
	v_mul_f32_e32 v161, v235, v161
	v_cvt_pk_bf16_f32 v204, v154, v155
	v_cvt_pk_bf16_f32 v205, v156, v157
	v_cvt_pk_bf16_f32 v206, v158, v159
	v_cvt_pk_bf16_f32 v207, v160, v161
	global_store_dwordx4 v137, v[204:207], s[26:27]
	s_barrier
	s_waitcnt vmcnt(0)
	ds_write_b32 v123, v140 offset:0
	ds_write_b32 v123, v141 offset:4
	ds_write_b32 v123, v142 offset:8
	ds_write_b32 v123, v143 offset:12
	ds_write_b32 v123, v150 offset:8320
	ds_write_b32 v123, v151 offset:8324
	ds_write_b32 v123, v152 offset:8328
	ds_write_b32 v123, v153 offset:8332
	s_waitcnt lgkmcnt(0)
	s_barrier
	s_mov_b64 s[26:27], s[16:17]
	ds_read_b32 v154, v136 offset:0
	ds_read_b32 v155, v136 offset:260
	ds_read_b32 v156, v136 offset:520
	ds_read_b32 v157, v136 offset:780
	ds_read_b32 v158, v136 offset:1040
	ds_read_b32 v159, v136 offset:1300
	ds_read_b32 v160, v136 offset:1560
	ds_read_b32 v161, v136 offset:1820
	s_waitcnt lgkmcnt(0)
	v_mul_f32_e32 v154, v235, v154
	v_mul_f32_e32 v155, v235, v155
	v_mul_f32_e32 v156, v235, v156
	v_mul_f32_e32 v157, v235, v157
	v_mul_f32_e32 v158, v235, v158
	v_mul_f32_e32 v159, v235, v159
	v_mul_f32_e32 v160, v235, v160
	v_mul_f32_e32 v161, v235, v161
	v_cvt_pk_bf16_f32 v204, v154, v155
	v_cvt_pk_bf16_f32 v205, v156, v157
	v_cvt_pk_bf16_f32 v206, v158, v159
	v_cvt_pk_bf16_f32 v207, v160, v161
	global_store_dwordx4 v137, v[204:207], s[26:27]
	s_barrier
	v_readlane_b32 s28, v253, 4
	v_readlane_b32 s29, v253, 5
	v_readlane_b32 s30, v253, 6
	v_readlane_b32 s31, v253, 7
	s_nop 3
	s_add_i32 s4, s2, 256
	s_cmpk_lt_u32 s4, 0x200
	s_cselect_b32 s6, s28, s30
	s_cselect_b32 s7, s29, s31
	s_mov_b32 s16, 0x10500000
	s_cselect_b32 s16, 0x10100000, s16
	s_bfe_u32 s5, s4, 0x10008
	s_lshl_b32 s3, s5, 22
	s_add_u32 s6, s6, s3
	s_addc_u32 s7, s7, 0
	s_lshl_b32 s3, s5, 21
	s_add_i32 s16, s16, s3
	s_and_b32 s3, s4, 15
	s_bfe_u32 s5, s4, 0x40004
	s_lshl_b32 s17, s3, 18
	s_lshl_b32 s20, s5, 8
	s_add_i32 s17, s17, s20
	s_add_u32 s6, s6, s17
	s_addc_u32 s7, s7, 0
	s_add_u32 s12, s6, 0x20000
	s_addc_u32 s13, s7, 0
	s_lshl_b32 s17, s5, 17
	s_lshl_b32 s20, s3, 7
	s_add_i32 s17, s17, s20
	s_add_i32 s16, s16, s17
	s_add_u32 s16, s96, s16
	s_addc_u32 s17, s97, 0
	global_load_dwordx4 v[140:143], v122, s[6:7]
	global_load_dwordx4 v[150:153], v122, s[12:13]
	s_waitcnt vmcnt(0)
	ds_write_b32 v123, v140 offset:0
	ds_write_b32 v123, v141 offset:4
	ds_write_b32 v123, v142 offset:8
	ds_write_b32 v123, v143 offset:12
	ds_write_b32 v123, v150 offset:8320
	ds_write_b32 v123, v151 offset:8324
	ds_write_b32 v123, v152 offset:8328
	ds_write_b32 v123, v153 offset:8332
	s_waitcnt lgkmcnt(0)
	s_barrier
	s_mov_b64 s[26:27], s[16:17]
	s_add_i32 s4, s2, 384
	s_cmpk_lt_u32 s4, 0x200
	s_cselect_b32 s6, s28, s30
	s_cselect_b32 s7, s29, s31
	s_mov_b32 s16, 0x10500000
	s_cselect_b32 s16, 0x10100000, s16
	s_bfe_u32 s5, s4, 0x10008
	s_lshl_b32 s3, s5, 22
	s_add_u32 s6, s6, s3
	s_addc_u32 s7, s7, 0
	s_lshl_b32 s3, s5, 21
	s_add_i32 s16, s16, s3
	s_and_b32 s3, s4, 15
	s_bfe_u32 s5, s4, 0x40004
	s_lshl_b32 s17, s3, 18
	s_lshl_b32 s20, s5, 8
	s_add_i32 s17, s17, s20
	s_add_u32 s6, s6, s17
	s_addc_u32 s7, s7, 0
	s_add_u32 s12, s6, 0x20000
	s_addc_u32 s13, s7, 0
	s_lshl_b32 s17, s5, 17
	s_lshl_b32 s20, s3, 7
	s_add_i32 s17, s17, s20
	s_add_i32 s16, s16, s17
	s_add_u32 s16, s96, s16
	s_addc_u32 s17, s97, 0
	global_load_dwordx4 v[140:143], v122, s[6:7]
	global_load_dwordx4 v[150:153], v122, s[12:13]
	ds_read_b32 v154, v136 offset:0
	ds_read_b32 v155, v136 offset:260
	ds_read_b32 v156, v136 offset:520
	ds_read_b32 v157, v136 offset:780
	ds_read_b32 v158, v136 offset:1040
	ds_read_b32 v159, v136 offset:1300
	ds_read_b32 v160, v136 offset:1560
	ds_read_b32 v161, v136 offset:1820
	s_waitcnt lgkmcnt(0)
	v_cvt_pk_bf16_f32 v204, v154, v155
	v_cvt_pk_bf16_f32 v205, v156, v157
	v_cvt_pk_bf16_f32 v206, v158, v159
	v_cvt_pk_bf16_f32 v207, v160, v161
	global_store_dwordx4 v137, v[204:207], s[26:27]
	s_barrier
	s_waitcnt vmcnt(0)
	ds_write_b32 v123, v140 offset:0
	ds_write_b32 v123, v141 offset:4
	ds_write_b32 v123, v142 offset:8
	ds_write_b32 v123, v143 offset:12
	ds_write_b32 v123, v150 offset:8320
	ds_write_b32 v123, v151 offset:8324
	ds_write_b32 v123, v152 offset:8328
	ds_write_b32 v123, v153 offset:8332
	s_waitcnt lgkmcnt(0)
	s_barrier
	s_mov_b64 s[26:27], s[16:17]
	s_add_i32 s4, s2, 768
	s_cmpk_lt_u32 s4, 0x200
	s_cselect_b32 s6, s28, s30
	s_cselect_b32 s7, s29, s31
	s_mov_b32 s16, 0x10500000
	s_cselect_b32 s16, 0x10100000, s16
	s_bfe_u32 s5, s4, 0x10008
	s_lshl_b32 s3, s5, 22
	s_add_u32 s6, s6, s3
	s_addc_u32 s7, s7, 0
	s_lshl_b32 s3, s5, 21
	s_add_i32 s16, s16, s3
	s_and_b32 s3, s4, 15
	s_bfe_u32 s5, s4, 0x40004
	s_lshl_b32 s17, s3, 18
	s_lshl_b32 s20, s5, 8
	s_add_i32 s17, s17, s20
	s_add_u32 s6, s6, s17
	s_addc_u32 s7, s7, 0
	s_add_u32 s12, s6, 0x20000
	s_addc_u32 s13, s7, 0
	s_lshl_b32 s17, s5, 17
	s_lshl_b32 s20, s3, 7
	s_add_i32 s17, s17, s20
	s_add_i32 s16, s16, s17
	s_add_u32 s16, s96, s16
	s_addc_u32 s17, s97, 0
	global_load_dwordx4 v[140:143], v122, s[6:7]
	global_load_dwordx4 v[150:153], v122, s[12:13]
	ds_read_b32 v154, v136 offset:0
	ds_read_b32 v155, v136 offset:260
	ds_read_b32 v156, v136 offset:520
	ds_read_b32 v157, v136 offset:780
	ds_read_b32 v158, v136 offset:1040
	ds_read_b32 v159, v136 offset:1300
	ds_read_b32 v160, v136 offset:1560
	ds_read_b32 v161, v136 offset:1820
	s_waitcnt lgkmcnt(0)
	v_cvt_pk_bf16_f32 v204, v154, v155
	v_cvt_pk_bf16_f32 v205, v156, v157
	v_cvt_pk_bf16_f32 v206, v158, v159
	v_cvt_pk_bf16_f32 v207, v160, v161
	global_store_dwordx4 v137, v[204:207], s[26:27]
	s_barrier
	s_waitcnt vmcnt(0)
	ds_write_b32 v123, v140 offset:0
	ds_write_b32 v123, v141 offset:4
	ds_write_b32 v123, v142 offset:8
	ds_write_b32 v123, v143 offset:12
	ds_write_b32 v123, v150 offset:8320
	ds_write_b32 v123, v151 offset:8324
	ds_write_b32 v123, v152 offset:8328
	ds_write_b32 v123, v153 offset:8332
	s_waitcnt lgkmcnt(0)
	s_barrier
	s_mov_b64 s[26:27], s[16:17]
	s_add_i32 s4, s2, 896
	s_cmpk_lt_u32 s4, 0x200
	s_cselect_b32 s6, s28, s30
	s_cselect_b32 s7, s29, s31
	s_mov_b32 s16, 0x10500000
	s_cselect_b32 s16, 0x10100000, s16
	s_bfe_u32 s5, s4, 0x10008
	s_lshl_b32 s3, s5, 22
	s_add_u32 s6, s6, s3
	s_addc_u32 s7, s7, 0
	s_lshl_b32 s3, s5, 21
	s_add_i32 s16, s16, s3
	s_and_b32 s3, s4, 15
	s_bfe_u32 s5, s4, 0x40004
	s_lshl_b32 s17, s3, 18
	s_lshl_b32 s20, s5, 8
	s_add_i32 s17, s17, s20
	s_add_u32 s6, s6, s17
	s_addc_u32 s7, s7, 0
	s_add_u32 s12, s6, 0x20000
	s_addc_u32 s13, s7, 0
	s_lshl_b32 s17, s5, 17
	s_lshl_b32 s20, s3, 7
	s_add_i32 s17, s17, s20
	s_add_i32 s16, s16, s17
	s_add_u32 s16, s96, s16
	s_addc_u32 s17, s97, 0
	global_load_dwordx4 v[140:143], v122, s[6:7]
	global_load_dwordx4 v[150:153], v122, s[12:13]
	ds_read_b32 v154, v136 offset:0
	ds_read_b32 v155, v136 offset:260
	ds_read_b32 v156, v136 offset:520
	ds_read_b32 v157, v136 offset:780
	ds_read_b32 v158, v136 offset:1040
	ds_read_b32 v159, v136 offset:1300
	ds_read_b32 v160, v136 offset:1560
	ds_read_b32 v161, v136 offset:1820
	s_waitcnt lgkmcnt(0)
	v_cvt_pk_bf16_f32 v204, v154, v155
	v_cvt_pk_bf16_f32 v205, v156, v157
	v_cvt_pk_bf16_f32 v206, v158, v159
	v_cvt_pk_bf16_f32 v207, v160, v161
	global_store_dwordx4 v137, v[204:207], s[26:27]
	s_barrier
	s_waitcnt vmcnt(0)
	ds_write_b32 v123, v140 offset:0
	ds_write_b32 v123, v141 offset:4
	ds_write_b32 v123, v142 offset:8
	ds_write_b32 v123, v143 offset:12
	ds_write_b32 v123, v150 offset:8320
	ds_write_b32 v123, v151 offset:8324
	ds_write_b32 v123, v152 offset:8328
	ds_write_b32 v123, v153 offset:8332
	s_waitcnt lgkmcnt(0)
	s_barrier
	s_mov_b64 s[26:27], s[16:17]
	ds_read_b32 v154, v136 offset:0
	ds_read_b32 v155, v136 offset:260
	ds_read_b32 v156, v136 offset:520
	ds_read_b32 v157, v136 offset:780
	ds_read_b32 v158, v136 offset:1040
	ds_read_b32 v159, v136 offset:1300
	ds_read_b32 v160, v136 offset:1560
	ds_read_b32 v161, v136 offset:1820
	s_waitcnt lgkmcnt(0)
	v_cvt_pk_bf16_f32 v204, v154, v155
	v_cvt_pk_bf16_f32 v205, v156, v157
	v_cvt_pk_bf16_f32 v206, v158, v159
	v_cvt_pk_bf16_f32 v207, v160, v161
	global_store_dwordx4 v137, v[204:207], s[26:27]
	s_barrier
